# attention diagonal tiles: causal mask + T5 bias look-ups made branch-free and read in two bursts of 8 instead of 16 serial exec-masked read-wait-add steps
# speedup vs baseline: 1.1437x; 1.0039x over previous
; #define LAS __attribute__((address_space(3)))
; __device__ __forceinline__ void attn_phase(LAS unsigned char* lds, const h16* Qb, const h16* Kb, const h16* Vt, h16* AO, const float* rel_bias, const float* lam, const float* subg, float lambda_init) {
;     ...
;             for (int kt = 0; kt < nkt; ++kt) {
;                 LAS unsigned char* cb = lds + (kt & 1) * STG; LAS unsigned char* nb = lds + ((kt & 1) ^ 1) * STG;
;                 const bool near = kt >= 2 * qb - 2;
;                 if (kt + 1 < nkt) ATT_ISSUE(kt + 1, nb);
; #pragma unroll
;                 for (int kb = 0; kb < 2; ++kb) {
;                     if (64 * kt + 32 * kb <= q0 + 32 * rg + 31) {
;                         f32x16 S0;
; #pragma unroll
;                         for (int r = 0; r < 16; ++r) S0[r] = 0.f;
;                         LAS unsigned char* ks = cb + (32 * kb + l32) * 512 + mp * 256;
; #pragma unroll
;                         for (int k = 0; k < 8; ++k) {
;                             const h16x8 a0 = *(LAS h16x8*)(ks + (((2 * k + hh) ^ xk) << 4));
;                             S0 = __builtin_amdgcn_mfma_f32_32x32x16_f16(a0, Qf[k], S0, 0, 0, 0);
;                         }
;                         if (near) {
; #pragma unroll
;                             for (int r = 0; r < 16; ++r) {
;                                 const int kp = 64 * kt + 32 * kb + (r >> 2) * 8 + hh * 4 + (r & 3); const int d0 = qrow - kp;
;                                 const int di = d0 < 0 ? 0 : (d0 > 128 ? 128 : d0); const float bv = lut[di];
;                                 S0[r] = d0 < 0 ? -1e30f : S0[r] + bv;
;                             }
;                         }
.LBB0_168:
	s_add_i32 s22, s21, 0
	s_cmp_ge_i32 s20, s35
	s_cselect_b64 s[20:21], -1, 0
	s_add_i32 s23, s22, s81
	v_add_u32_e32 v0, s23, v226
	v_cndmask_b32_e64 v2, 0, 1, s[20:21]
	v_add_u32_e32 v10, s22, v225
	s_cmp_gt_i32 s50, s48
	v_add_u32_e32 v213, v0, v227
	v_add_u32_e32 v212, v0, v228
	v_add_u32_e32 v245, v0, v229
	v_add_u32_e32 v15, v0, v230
	v_add_u32_e32 v14, v0, v231
	v_add_u32_e32 v13, v0, v232
	v_add_u32_e32 v12, v0, v233
	v_add_u32_e32 v11, v0, v234
	v_cmp_ne_u32_e64 s[38:39], 1, v2
	s_mov_b64 vcc, s[20:21]
	s_cbranch_vccz .Lattn_fast
	s_cbranch_scc1 .LBB0_206
	ds_read_b128 v[160:163], v213
	ds_read_b128 v[164:167], v212
	ds_read_b128 v[168:171], v245
	ds_read_b128 v[172:175], v15
	s_and_b64 vcc, exec, s[38:39]
	s_waitcnt lgkmcnt(3)
	v_mfma_f32_32x32x16_f16 v[144:159], v[160:163], v[176:179], 0
	ds_read_b128 v[160:163], v14
	s_waitcnt lgkmcnt(3)
	v_mfma_f32_32x32x16_f16 v[144:159], v[164:167], v[180:183], v[144:159]
	ds_read_b128 v[164:167], v13
	s_waitcnt lgkmcnt(3)
	v_mfma_f32_32x32x16_f16 v[144:159], v[168:171], v[184:187], v[144:159]
	ds_read_b128 v[168:171], v12
	s_waitcnt lgkmcnt(3)
	v_mfma_f32_32x32x16_f16 v[144:159], v[172:175], v[188:191], v[144:159]
	ds_read_b128 v[172:175], v11
	s_waitcnt lgkmcnt(3)
	v_mfma_f32_32x32x16_f16 v[144:159], v[160:163], v[192:195], v[144:159]
	s_waitcnt lgkmcnt(2)
	v_mfma_f32_32x32x16_f16 v[144:159], v[164:167], v[196:199], v[144:159]
	s_waitcnt lgkmcnt(1)
	v_mfma_f32_32x32x16_f16 v[144:159], v[168:171], v[200:203], v[144:159]
	s_waitcnt lgkmcnt(0)
	v_mfma_f32_32x32x16_f16 v[144:159], v[172:175], v[204:207], v[144:159]
	s_cbranch_vccnz .LBB0_203
	v_mov_b32_e32 v0, 0xf149f2ca
	v_add_u32_e32 v160, 27, v239
	v_max_i32_e32 v2, 0, v160
	v_min_u32_e32 v2, 0x80, v2
	v_lshlrev_b32_e32 v2, 2, v2
	v_add_u32_e32 v2, 0x20000, v2
	ds_read_b32 v2, v2
	v_add_u32_e32 v161, 26, v239
	v_max_i32_e32 v3, 0, v161
	v_min_u32_e32 v3, 0x80, v3
	v_lshlrev_b32_e32 v3, 2, v3
	v_add_u32_e32 v3, 0x20000, v3
	ds_read_b32 v3, v3
	v_add_u32_e32 v162, 25, v239
	v_max_i32_e32 v4, 0, v162
	v_min_u32_e32 v4, 0x80, v4
	v_lshlrev_b32_e32 v4, 2, v4
	v_add_u32_e32 v4, 0x20000, v4
	ds_read_b32 v4, v4
	v_add_u32_e32 v163, 24, v239
	v_max_i32_e32 v5, 0, v163
	v_min_u32_e32 v5, 0x80, v5
	v_lshlrev_b32_e32 v5, 2, v5
	v_add_u32_e32 v5, 0x20000, v5
	ds_read_b32 v5, v5
	v_add_u32_e32 v164, 19, v239
	v_max_i32_e32 v6, 0, v164
	v_min_u32_e32 v6, 0x80, v6
	v_lshlrev_b32_e32 v6, 2, v6
	v_add_u32_e32 v6, 0x20000, v6
	ds_read_b32 v6, v6
	v_add_u32_e32 v165, 18, v239
	v_max_i32_e32 v7, 0, v165
	v_min_u32_e32 v7, 0x80, v7
	v_lshlrev_b32_e32 v7, 2, v7
	v_add_u32_e32 v7, 0x20000, v7
	ds_read_b32 v7, v7
	v_add_u32_e32 v166, 17, v239
	v_max_i32_e32 v8, 0, v166
	v_min_u32_e32 v8, 0x80, v8
	v_lshlrev_b32_e32 v8, 2, v8
	v_add_u32_e32 v8, 0x20000, v8
	ds_read_b32 v8, v8
	v_add_u32_e32 v167, 16, v239
	v_max_i32_e32 v9, 0, v167
	v_min_u32_e32 v9, 0x80, v9
	v_lshlrev_b32_e32 v9, 2, v9
	v_add_u32_e32 v9, 0x20000, v9
	ds_read_b32 v9, v9
	s_waitcnt lgkmcnt(0)
	v_cmp_lt_i32_e32 vcc, -1, v160
	v_add_f32_e32 v2, v144, v2
	s_nop 0
	v_cndmask_b32_e32 v144, v0, v2, vcc
	v_cmp_lt_i32_e32 vcc, -1, v161
	v_add_f32_e32 v3, v145, v3
	s_nop 0
	v_cndmask_b32_e32 v145, v0, v3, vcc
	v_cmp_lt_i32_e32 vcc, -1, v162
	v_add_f32_e32 v4, v146, v4
	s_nop 0
	v_cndmask_b32_e32 v146, v0, v4, vcc
	v_cmp_lt_i32_e32 vcc, -1, v163
	v_add_f32_e32 v5, v147, v5
	s_nop 0
	v_cndmask_b32_e32 v147, v0, v5, vcc
	v_cmp_lt_i32_e32 vcc, -1, v164
	v_add_f32_e32 v6, v148, v6
	s_nop 0
	v_cndmask_b32_e32 v148, v0, v6, vcc
	v_cmp_lt_i32_e32 vcc, -1, v165
	v_add_f32_e32 v7, v149, v7
	s_nop 0
	v_cndmask_b32_e32 v149, v0, v7, vcc
	v_cmp_lt_i32_e32 vcc, -1, v166
	v_add_f32_e32 v8, v150, v8
	s_nop 0
	v_cndmask_b32_e32 v150, v0, v8, vcc
	v_cmp_lt_i32_e32 vcc, -1, v167
	v_add_f32_e32 v9, v151, v9
	s_nop 0
	v_cndmask_b32_e32 v151, v0, v9, vcc
	v_add_u32_e32 v168, 11, v239
	v_max_i32_e32 v2, 0, v168
	v_min_u32_e32 v2, 0x80, v2
	v_lshlrev_b32_e32 v2, 2, v2
	v_add_u32_e32 v2, 0x20000, v2
	ds_read_b32 v2, v2
	v_add_u32_e32 v169, 10, v239
	v_max_i32_e32 v3, 0, v169
	v_min_u32_e32 v3, 0x80, v3
	v_lshlrev_b32_e32 v3, 2, v3
	v_add_u32_e32 v3, 0x20000, v3
	ds_read_b32 v3, v3
	v_add_u32_e32 v170, 9, v239
	v_max_i32_e32 v4, 0, v170
	v_min_u32_e32 v4, 0x80, v4
	v_lshlrev_b32_e32 v4, 2, v4
	v_add_u32_e32 v4, 0x20000, v4
	ds_read_b32 v4, v4
	v_add_u32_e32 v171, 8, v239
	v_max_i32_e32 v5, 0, v171
	v_min_u32_e32 v5, 0x80, v5
	v_lshlrev_b32_e32 v5, 2, v5
	v_add_u32_e32 v5, 0x20000, v5
	ds_read_b32 v5, v5
	v_add_u32_e32 v172, 3, v239
	v_max_i32_e32 v6, 0, v172
	v_min_u32_e32 v6, 0x80, v6
	v_lshlrev_b32_e32 v6, 2, v6
	v_add_u32_e32 v6, 0x20000, v6
	ds_read_b32 v6, v6
	v_add_u32_e32 v173, 2, v239
	v_max_i32_e32 v7, 0, v173
	v_min_u32_e32 v7, 0x80, v7
	v_lshlrev_b32_e32 v7, 2, v7
	v_add_u32_e32 v7, 0x20000, v7
	ds_read_b32 v7, v7
	v_add_u32_e32 v174, 1, v239
	v_max_i32_e32 v8, 0, v174
	v_min_u32_e32 v8, 0x80, v8
	v_lshlrev_b32_e32 v8, 2, v8
	v_add_u32_e32 v8, 0x20000, v8
	ds_read_b32 v8, v8
	v_mov_b32_e32 v175, v239
	v_max_i32_e32 v9, 0, v175
	v_min_u32_e32 v9, 0x80, v9
	v_lshlrev_b32_e32 v9, 2, v9
	v_add_u32_e32 v9, 0x20000, v9
	ds_read_b32 v9, v9
	s_waitcnt lgkmcnt(0)
	v_cmp_lt_i32_e32 vcc, -1, v168
	v_add_f32_e32 v2, v152, v2
	s_nop 0
	v_cndmask_b32_e32 v152, v0, v2, vcc
	v_cmp_lt_i32_e32 vcc, -1, v169
	v_add_f32_e32 v3, v153, v3
	s_nop 0
	v_cndmask_b32_e32 v153, v0, v3, vcc
	v_cmp_lt_i32_e32 vcc, -1, v170
	v_add_f32_e32 v4, v154, v4
	s_nop 0
	v_cndmask_b32_e32 v154, v0, v4, vcc
	v_cmp_lt_i32_e32 vcc, -1, v171
	v_add_f32_e32 v5, v155, v5
	s_nop 0
	v_cndmask_b32_e32 v155, v0, v5, vcc
	v_cmp_lt_i32_e32 vcc, -1, v172
	v_add_f32_e32 v6, v156, v6
	s_nop 0
	v_cndmask_b32_e32 v156, v0, v6, vcc
	v_cmp_lt_i32_e32 vcc, -1, v173
	v_add_f32_e32 v7, v157, v7
	s_nop 0
	v_cndmask_b32_e32 v157, v0, v7, vcc
	v_cmp_lt_i32_e32 vcc, -1, v174
	v_add_f32_e32 v8, v158, v8
	s_nop 0
	v_cndmask_b32_e32 v158, v0, v8, vcc
	v_cmp_lt_i32_e32 vcc, -1, v175
	v_add_f32_e32 v9, v159, v9
	s_nop 0
	v_cndmask_b32_e32 v159, v0, v9, vcc

; #define LAS __attribute__((address_space(3)))
; __device__ __forceinline__ void attn_phase(LAS unsigned char* lds, const h16* Qb, const h16* Kb, const h16* Vt, h16* AO, const float* rel_bias, const float* lam, const float* subg, float lambda_init) {
;     ...
;                     if (64 * kt + 32 * kb <= q0 + 32 * rg + 31) {
;                         f32x16 S0;
; #pragma unroll
;                         for (int r = 0; r < 16; ++r) S0[r] = 0.f;
;                         LAS unsigned char* ks = cb + (32 * kb + l32) * 512 + mp * 256;
; #pragma unroll
;                         for (int k = 0; k < 8; ++k) {
;                             const h16x8 a0 = *(LAS h16x8*)(ks + (((2 * k + hh) ^ xk) << 4));
;                             S0 = __builtin_amdgcn_mfma_f32_32x32x16_f16(a0, Qf[k], S0, 0, 0, 0);
;                         }
;                         if (near) {
; #pragma unroll
;                             for (int r = 0; r < 16; ++r) {
;                                 const int kp = 64 * kt + 32 * kb + (r >> 2) * 8 + hh * 4 + (r & 3); const int d0 = qrow - kp;
;                                 const int di = d0 < 0 ? 0 : (d0 > 128 ? 128 : d0); const float bv = lut[di];
;                                 S0[r] = d0 < 0 ? -1e30f : S0[r] + bv;
;                             }
;                         }
.LBB0_206:
	s_add_i32 s20, s50, 32
	s_cmp_gt_i32 s20, s48
	s_cbranch_scc1 .LBB0_244
	ds_read_b128 v[160:163], v213 offset:16384
	ds_read_b128 v[164:167], v212 offset:16384
	ds_read_b128 v[168:171], v245 offset:16384
	ds_read_b128 v[172:175], v15 offset:16384
	s_and_b64 vcc, exec, s[38:39]
	s_waitcnt lgkmcnt(3)
	v_mfma_f32_32x32x16_f16 v[144:159], v[160:163], v[176:179], 0
	ds_read_b128 v[160:163], v14 offset:16384
	s_waitcnt lgkmcnt(3)
	v_mfma_f32_32x32x16_f16 v[144:159], v[164:167], v[180:183], v[144:159]
	ds_read_b128 v[164:167], v13 offset:16384
	s_waitcnt lgkmcnt(3)
	v_mfma_f32_32x32x16_f16 v[144:159], v[168:171], v[184:187], v[144:159]
	ds_read_b128 v[168:171], v12 offset:16384
	s_waitcnt lgkmcnt(3)
	v_mfma_f32_32x32x16_f16 v[144:159], v[172:175], v[188:191], v[144:159]
	ds_read_b128 v[172:175], v11 offset:16384
	s_waitcnt lgkmcnt(3)
	v_mfma_f32_32x32x16_f16 v[144:159], v[160:163], v[192:195], v[144:159]
	s_waitcnt lgkmcnt(2)
	v_mfma_f32_32x32x16_f16 v[144:159], v[164:167], v[196:199], v[144:159]
	s_waitcnt lgkmcnt(1)
	v_mfma_f32_32x32x16_f16 v[144:159], v[168:171], v[200:203], v[144:159]
	s_waitcnt lgkmcnt(0)
	v_mfma_f32_32x32x16_f16 v[144:159], v[172:175], v[204:207], v[144:159]
	s_cbranch_vccnz .LBB0_241
	v_mov_b32_e32 v0, 0xf149f2ca
	v_add_u32_e32 v160, -5, v239
	v_max_i32_e32 v2, 0, v160
	v_min_u32_e32 v2, 0x80, v2
	v_lshlrev_b32_e32 v2, 2, v2
	v_add_u32_e32 v2, 0x20000, v2
	ds_read_b32 v2, v2
	v_add_u32_e32 v161, -6, v239
	v_max_i32_e32 v3, 0, v161
	v_min_u32_e32 v3, 0x80, v3
	v_lshlrev_b32_e32 v3, 2, v3
	v_add_u32_e32 v3, 0x20000, v3
	ds_read_b32 v3, v3
	v_add_u32_e32 v162, -7, v239
	v_max_i32_e32 v4, 0, v162
	v_min_u32_e32 v4, 0x80, v4
	v_lshlrev_b32_e32 v4, 2, v4
	v_add_u32_e32 v4, 0x20000, v4
	ds_read_b32 v4, v4
	v_add_u32_e32 v163, -8, v239
	v_max_i32_e32 v5, 0, v163
	v_min_u32_e32 v5, 0x80, v5
	v_lshlrev_b32_e32 v5, 2, v5
	v_add_u32_e32 v5, 0x20000, v5
	ds_read_b32 v5, v5
	v_add_u32_e32 v164, -13, v239
	v_max_i32_e32 v6, 0, v164
	v_min_u32_e32 v6, 0x80, v6
	v_lshlrev_b32_e32 v6, 2, v6
	v_add_u32_e32 v6, 0x20000, v6
	ds_read_b32 v6, v6
	v_add_u32_e32 v165, -14, v239
	v_max_i32_e32 v7, 0, v165
	v_min_u32_e32 v7, 0x80, v7
	v_lshlrev_b32_e32 v7, 2, v7
	v_add_u32_e32 v7, 0x20000, v7
	ds_read_b32 v7, v7
	v_add_u32_e32 v166, -15, v239
	v_max_i32_e32 v8, 0, v166
	v_min_u32_e32 v8, 0x80, v8
	v_lshlrev_b32_e32 v8, 2, v8
	v_add_u32_e32 v8, 0x20000, v8
	ds_read_b32 v8, v8
	v_add_u32_e32 v167, -16, v239
	v_max_i32_e32 v9, 0, v167
	v_min_u32_e32 v9, 0x80, v9
	v_lshlrev_b32_e32 v9, 2, v9
	v_add_u32_e32 v9, 0x20000, v9
	ds_read_b32 v9, v9
	s_waitcnt lgkmcnt(0)
	v_cmp_lt_i32_e32 vcc, -1, v160
	v_add_f32_e32 v2, v144, v2
	s_nop 0
	v_cndmask_b32_e32 v144, v0, v2, vcc
	v_cmp_lt_i32_e32 vcc, -1, v161
	v_add_f32_e32 v3, v145, v3
	s_nop 0
	v_cndmask_b32_e32 v145, v0, v3, vcc
	v_cmp_lt_i32_e32 vcc, -1, v162
	v_add_f32_e32 v4, v146, v4
	s_nop 0
	v_cndmask_b32_e32 v146, v0, v4, vcc
	v_cmp_lt_i32_e32 vcc, -1, v163
	v_add_f32_e32 v5, v147, v5
	s_nop 0
	v_cndmask_b32_e32 v147, v0, v5, vcc
	v_cmp_lt_i32_e32 vcc, -1, v164
	v_add_f32_e32 v6, v148, v6
	s_nop 0
	v_cndmask_b32_e32 v148, v0, v6, vcc
	v_cmp_lt_i32_e32 vcc, -1, v165
	v_add_f32_e32 v7, v149, v7
	s_nop 0
	v_cndmask_b32_e32 v149, v0, v7, vcc
	v_cmp_lt_i32_e32 vcc, -1, v166
	v_add_f32_e32 v8, v150, v8
	s_nop 0
	v_cndmask_b32_e32 v150, v0, v8, vcc
	v_cmp_lt_i32_e32 vcc, -1, v167
	v_add_f32_e32 v9, v151, v9
	s_nop 0
	v_cndmask_b32_e32 v151, v0, v9, vcc
	v_add_u32_e32 v168, -21, v239
	v_max_i32_e32 v2, 0, v168
	v_min_u32_e32 v2, 0x80, v2
	v_lshlrev_b32_e32 v2, 2, v2
	v_add_u32_e32 v2, 0x20000, v2
	ds_read_b32 v2, v2
	v_add_u32_e32 v169, -22, v239
	v_max_i32_e32 v3, 0, v169
	v_min_u32_e32 v3, 0x80, v3
	v_lshlrev_b32_e32 v3, 2, v3
	v_add_u32_e32 v3, 0x20000, v3
	ds_read_b32 v3, v3
	v_add_u32_e32 v170, -23, v239
	v_max_i32_e32 v4, 0, v170
	v_min_u32_e32 v4, 0x80, v4
	v_lshlrev_b32_e32 v4, 2, v4
	v_add_u32_e32 v4, 0x20000, v4
	ds_read_b32 v4, v4
	v_add_u32_e32 v171, -24, v239
	v_max_i32_e32 v5, 0, v171
	v_min_u32_e32 v5, 0x80, v5
	v_lshlrev_b32_e32 v5, 2, v5
	v_add_u32_e32 v5, 0x20000, v5
	ds_read_b32 v5, v5
	v_add_u32_e32 v172, -29, v239
	v_max_i32_e32 v6, 0, v172
	v_min_u32_e32 v6, 0x80, v6
	v_lshlrev_b32_e32 v6, 2, v6
	v_add_u32_e32 v6, 0x20000, v6
	ds_read_b32 v6, v6
	v_add_u32_e32 v173, -30, v239
	v_max_i32_e32 v7, 0, v173
	v_min_u32_e32 v7, 0x80, v7
	v_lshlrev_b32_e32 v7, 2, v7
	v_add_u32_e32 v7, 0x20000, v7
	ds_read_b32 v7, v7
	v_add_u32_e32 v174, -31, v239
	v_max_i32_e32 v8, 0, v174
	v_min_u32_e32 v8, 0x80, v8
	v_lshlrev_b32_e32 v8, 2, v8
	v_add_u32_e32 v8, 0x20000, v8
	ds_read_b32 v8, v8
	v_add_u32_e32 v175, -32, v239
	v_max_i32_e32 v9, 0, v175
	v_min_u32_e32 v9, 0x80, v9
	v_lshlrev_b32_e32 v9, 2, v9
	v_add_u32_e32 v9, 0x20000, v9
	ds_read_b32 v9, v9
	s_waitcnt lgkmcnt(0)
	v_cmp_lt_i32_e32 vcc, -1, v168
	v_add_f32_e32 v2, v152, v2
	s_nop 0
	v_cndmask_b32_e32 v152, v0, v2, vcc
	v_cmp_lt_i32_e32 vcc, -1, v169
	v_add_f32_e32 v3, v153, v3
	s_nop 0
	v_cndmask_b32_e32 v153, v0, v3, vcc
	v_cmp_lt_i32_e32 vcc, -1, v170
	v_add_f32_e32 v4, v154, v4
	s_nop 0
	v_cndmask_b32_e32 v154, v0, v4, vcc
	v_cmp_lt_i32_e32 vcc, -1, v171
	v_add_f32_e32 v5, v155, v5
	s_nop 0
	v_cndmask_b32_e32 v155, v0, v5, vcc
	v_cmp_lt_i32_e32 vcc, -1, v172
	v_add_f32_e32 v6, v156, v6
	s_nop 0
	v_cndmask_b32_e32 v156, v0, v6, vcc
	v_cmp_lt_i32_e32 vcc, -1, v173
	v_add_f32_e32 v7, v157, v7
	s_nop 0
	v_cndmask_b32_e32 v157, v0, v7, vcc
	v_cmp_lt_i32_e32 vcc, -1, v174
	v_add_f32_e32 v8, v158, v8
	s_nop 0
	v_cndmask_b32_e32 v158, v0, v8, vcc
	v_cmp_lt_i32_e32 vcc, -1, v175
	v_add_f32_e32 v9, v159, v9
	s_nop 0
	v_cndmask_b32_e32 v159, v0, v9, vcc
